# pool unit: skip Wpool fragment loads in the 6 waves that never use them
# speedup vs baseline: 1.0131x; 1.0048x over previous
.LBB0_594:
	s_or_b64 exec, exec, s[48:49]
	s_mov_b32 s37, s73
	s_lshl_b64 s[24:25], s[36:37], 15
	s_add_u32 s24, s51, s24
	v_readlane_b32 s12, v253, 20
	v_bfe_u32 v225, v161, 4, 2
	s_addc_u32 s25, s12, s25
	v_lshlrev_b32_e32 v0, 8, v176
	v_lshl_add_u64 v[2:3], s[24:25], 0, v[0:1]
	v_lshlrev_b32_e32 v0, 4, v225
	v_lshl_add_u64 v[2:3], v[2:3], 0, v[0:1]
	v_lshlrev_b32_e32 v151, 4, v161
	v_and_b32_e32 v151, 0xf0, v151
	v_readfirstlane_b32 s12, v161
	s_cmpk_gt_i32 s12, 0x7f
	s_cbranch_scc1 .Lpw_skip
	s_movk_i32 s12, 0x1000
	v_add_co_u32_e32 v4, vcc, s12, v2
	s_movk_i32 s12, 0x2000
	s_nop 0
	v_addc_co_u32_e32 v5, vcc, 0, v3, vcc
	v_add_co_u32_e32 v126, vcc, s12, v2
	s_movk_i32 s12, 0x3000
	s_nop 0
	v_addc_co_u32_e32 v127, vcc, 0, v3, vcc
	v_add_co_u32_e32 v6, vcc, s12, v2
	s_movk_i32 s12, 0x4000
	s_nop 0
	v_addc_co_u32_e32 v7, vcc, 0, v3, vcc
	v_add_co_u32_e32 v8, vcc, s12, v2
	s_movk_i32 s12, 0x5000
	s_nop 0
	v_addc_co_u32_e32 v9, vcc, 0, v3, vcc
	global_load_dwordx4 v[98:101], v[2:3], off
	global_load_dwordx4 v[78:81], v[2:3], off offset:64
	global_load_dwordx4 v[66:69], v[2:3], off offset:128
	global_load_dwordx4 v[34:37], v[2:3], off offset:192
	global_load_dwordx4 v[70:73], v[4:5], off offset:64
	global_load_dwordx4 v[74:77], v[4:5], off offset:128
	global_load_dwordx4 v[38:41], v[126:127], off
	global_load_dwordx4 v[42:45], v[126:127], off offset:64
	global_load_dwordx4 v[46:49], v[126:127], off offset:128
	global_load_dwordx4 v[50:53], v[126:127], off offset:192
	global_load_dwordx4 v[122:125], v[4:5], off offset:192
	global_load_dwordx4 v[82:85], v[6:7], off offset:64
	global_load_dwordx4 v[86:89], v[6:7], off offset:128
	global_load_dwordx4 v[90:93], v[6:7], off offset:192
	global_load_dwordx4 v[102:105], v[8:9], off offset:-4096
	global_load_dwordx4 v[54:57], v[8:9], off
	global_load_dwordx4 v[58:61], v[8:9], off offset:64
	global_load_dwordx4 v[62:65], v[8:9], off offset:128
	v_add_co_u32_e32 v4, vcc, s12, v2
	s_movk_i32 s12, 0x6000
	s_nop 0
	v_addc_co_u32_e32 v5, vcc, 0, v3, vcc
	v_add_co_u32_e32 v6, vcc, s12, v2
	s_nop 0
	v_addc_co_u32_e32 v7, vcc, 0, v3, vcc
	global_load_dwordx4 v[118:121], v[8:9], off offset:192
	global_load_dwordx4 v[110:113], v[6:7], off offset:-4096
	global_load_dwordx4 v[106:109], v[4:5], off offset:64
	global_load_dwordx4 v[94:97], v[4:5], off offset:128
	global_load_dwordx4 v[30:33], v[6:7], off
	global_load_dwordx4 v[26:29], v[6:7], off offset:64
	global_load_dwordx4 v[22:25], v[6:7], off offset:128
	global_load_dwordx4 v[18:21], v[6:7], off offset:192
	v_add_co_u32_e32 v2, vcc, 0x7000, v2
	s_nop 0
	v_addc_co_u32_e32 v3, vcc, 0, v3, vcc
	global_load_dwordx4 v[114:117], v[4:5], off offset:192
	global_load_dwordx4 v[14:17], v[2:3], off
	global_load_dwordx4 v[10:13], v[2:3], off offset:64
	global_load_dwordx4 v[6:9], v[2:3], off offset:128
	s_nop 0
	global_load_dwordx4 v[126:129], v[126:127], off offset:-4096
	s_nop 0
	global_load_dwordx4 v[2:5], v[2:3], off offset:192
.Lpw_skip:
	v_add_u32_e32 v160, 0, v151
	s_and_saveexec_b64 s[48:49], s[0:1]
	s_cbranch_execz .LBB0_613
	s_movk_i32 s0, 0x120
	v_mad_u64_u32 v[150:151], s[0:1], v150, s0, v[160:161]
	s_waitcnt vmcnt(0)
	ds_write_b128 v150, v[134:137]
	s_or_b64 exec, exec, s[48:49]
	s_and_saveexec_b64 s[0:1], s[38:39]
	s_cbranch_execnz .LBB0_614
